# prompt attention tail: bf16 P-fragment conversions interleaved with the PV MFMAs (later k-steps converted in the MFMA shadow); on top of v36
# speedup vs baseline: 1.0081x; 1.0023x over previous
; __device__ __forceinline__ unsigned pk2(float lo, float hi) { f32x2_t v = {lo, hi}; bf16x2_t b = __builtin_convertvector(v, bf16x2_t); return __builtin_bit_cast(unsigned, b); }
; template <bool SAMPLE>
; __device__ __forceinline__ void attn_unit(const Params& p, LAS unsigned char* lds, int unit, int tid, int lane, int wave, float thr) {
;     ...
;             float mx = fmaxf(sA[0], sB[0]);
; #pragma unroll
;             for (int r = 1; r < 16; ++r) mx = fmaxf(mx, fmaxf(sA[r], sB[r]));
;             mx = fmaxf(mx, __shfl_xor(mx, 32));
;             const float mnew = fmaxf(mrun, mx); const float alpha = __builtin_amdgcn_exp2f(mrun - mnew); mrun = mnew;
;             float ls = 0.f;
; #pragma unroll
;             for (int r = 0; r < 16; ++r) { sA[r] = __builtin_amdgcn_exp2f(sA[r] - mnew); sB[r] = __builtin_amdgcn_exp2f(sB[r] - mnew); ls += sA[r] + sB[r]; }
;             lrun = lrun * alpha + ls;
; #pragma unroll
;             for (int r = 0; r < 16; ++r) { o0[r] *= alpha; o1[r] *= alpha; }
;             bf16x8 pf[4];
;             { u32x4 w;
;               w.x = pk2(sA[0], sA[1]); w.y = pk2(sA[2], sA[3]); w.z = pk2(sA[4], sA[5]); w.w = pk2(sA[6], sA[7]); pf[0] = __builtin_bit_cast(bf16x8, w);
;               w.x = pk2(sA[8], sA[9]); w.y = pk2(sA[10], sA[11]); w.z = pk2(sA[12], sA[13]); w.w = pk2(sA[14], sA[15]); pf[1] = __builtin_bit_cast(bf16x8, w);
;               w.x = pk2(sB[0], sB[1]); w.y = pk2(sB[2], sB[3]); w.z = pk2(sB[4], sB[5]); w.w = pk2(sB[6], sB[7]); pf[2] = __builtin_bit_cast(bf16x8, w);
;               w.x = pk2(sB[8], sB[9]); w.y = pk2(sB[10], sB[11]); w.z = pk2(sB[12], sB[13]); w.w = pk2(sB[14], sB[15]); pf[3] = __builtin_bit_cast(bf16x8, w); }
; #pragma unroll
;             for (int ks = 0; ks < 4; ++ks) {
;                 const s16x4 a0 = vtr(vbase + (16 * ks) * KROW), a1 = vtr(vbase + (16 * ks + 8) * KROW);
;                 const s16x4 c0 = vtr(vbase + (16 * ks) * KROW + 64), c1 = vtr(vbase + (16 * ks + 8) * KROW + 64);
;                 const bf16x8 va = (bf16x8){a0[0], a0[1], a0[2], a0[3], a1[0], a1[1], a1[2], a1[3]}, vc = (bf16x8){c0[0], c0[1], c0[2], c0[3], c1[0], c1[1], c1[2], c1[3]};
;                 o0 = __builtin_amdgcn_mfma_f32_32x32x16_bf16(va, pf[ks], o0, 0, 0, 0); o1 = __builtin_amdgcn_mfma_f32_32x32x16_bf16(vc, pf[ks], o1, 0, 0, 0);
;             }
.LBB0_619:
	ds_read_b64_tr_b16 v[114:115], v111 offset:9216
	ds_read_b64_tr_b16 v[116:117], v111 offset:10368
	ds_read_b64_tr_b16 v[118:119], v111 offset:9280
	ds_read_b64_tr_b16 v[120:121], v111 offset:10432
	ds_read_b64_tr_b16 v[122:123], v111 offset:11520
	ds_read_b64_tr_b16 v[124:125], v111 offset:12672
	ds_read_b64_tr_b16 v[126:127], v111 offset:11584
	ds_read_b64_tr_b16 v[128:129], v111 offset:12736
	ds_read_b64_tr_b16 v[238:239], v111 offset:13824
	ds_read_b64_tr_b16 v[240:241], v111 offset:14976
	ds_read_b64_tr_b16 v[242:243], v111 offset:13888
	ds_read_b64_tr_b16 v[244:245], v111 offset:15040
	ds_read_b64_tr_b16 v[246:247], v111 offset:16128
	ds_read_b64_tr_b16 v[248:249], v111 offset:17280
	ds_read_b64_tr_b16 v[250:251], v111 offset:16192
	ds_read_b64_tr_b16 v[252:253], v111 offset:17344
	v_max3_f32 v2, v54, v55, v56
	v_max3_f32 v3, v38, v39, v40
	v_max3_f32 v2, v2, v57, v58
	v_max3_f32 v3, v3, v41, v42
	v_max3_f32 v2, v2, v59, v60
	v_max3_f32 v3, v3, v43, v44
	v_max3_f32 v2, v2, v61, v62
	v_max3_f32 v3, v3, v45, v46
	v_max3_f32 v2, v2, v63, v64
	v_max3_f32 v3, v3, v47, v48
	v_max3_f32 v2, v2, v65, v66
	v_max3_f32 v3, v3, v49, v50
	v_max3_f32 v2, v2, v67, v68
	v_max3_f32 v3, v3, v51, v52
	v_max3_f32 v2, v2, v3, v69
	v_max_f32_e32 v2, v2, v53
	v_mov_b32_e32 v3, v2
	s_nop 1
	v_permlane32_swap_b32_e32 v2, v3
	v_max3_f32 v3, v113, v2, v3
	v_sub_f32_e32 v54, v54, v3
	v_sub_f32_e32 v55, v55, v3
	v_exp_f32_e32 v54, v54
	v_exp_f32_e32 v55, v55
	v_sub_f32_e32 v56, v56, v3
	v_sub_f32_e32 v57, v57, v3
	v_exp_f32_e32 v56, v56
	v_exp_f32_e32 v57, v57
	v_sub_f32_e32 v58, v58, v3
	v_sub_f32_e32 v59, v59, v3
	v_exp_f32_e32 v58, v58
	v_exp_f32_e32 v59, v59
	v_sub_f32_e32 v60, v60, v3
	v_sub_f32_e32 v61, v61, v3
	v_exp_f32_e32 v60, v60
	v_exp_f32_e32 v61, v61
	v_sub_f32_e32 v62, v62, v3
	v_sub_f32_e32 v63, v63, v3
	v_exp_f32_e32 v62, v62
	v_exp_f32_e32 v63, v63
	v_sub_f32_e32 v64, v64, v3
	v_sub_f32_e32 v65, v65, v3
	v_exp_f32_e32 v64, v64
	v_exp_f32_e32 v65, v65
	v_sub_f32_e32 v66, v66, v3
	v_sub_f32_e32 v67, v67, v3
	v_exp_f32_e32 v66, v66
	v_exp_f32_e32 v67, v67
	v_sub_f32_e32 v68, v68, v3
	v_sub_f32_e32 v69, v69, v3
	v_exp_f32_e32 v68, v68
	v_exp_f32_e32 v69, v69
	v_sub_f32_e32 v38, v38, v3
	v_sub_f32_e32 v39, v39, v3
	v_exp_f32_e32 v38, v38
	v_exp_f32_e32 v39, v39
	v_sub_f32_e32 v40, v40, v3
	v_sub_f32_e32 v41, v41, v3
	v_exp_f32_e32 v40, v40
	v_exp_f32_e32 v41, v41
	v_sub_f32_e32 v42, v42, v3
	v_sub_f32_e32 v43, v43, v3
	v_exp_f32_e32 v42, v42
	v_exp_f32_e32 v43, v43
	v_sub_f32_e32 v44, v44, v3
	v_sub_f32_e32 v45, v45, v3
	v_exp_f32_e32 v44, v44
	v_exp_f32_e32 v45, v45
	v_sub_f32_e32 v46, v46, v3
	v_sub_f32_e32 v47, v47, v3
	v_exp_f32_e32 v46, v46
	v_exp_f32_e32 v47, v47
	v_sub_f32_e32 v48, v48, v3
	v_sub_f32_e32 v49, v49, v3
	v_exp_f32_e32 v48, v48
	v_exp_f32_e32 v49, v49
	v_sub_f32_e32 v50, v50, v3
	v_sub_f32_e32 v51, v51, v3
	v_exp_f32_e32 v50, v50
	v_exp_f32_e32 v51, v51
	v_sub_f32_e32 v52, v52, v3
	v_sub_f32_e32 v53, v53, v3
	v_exp_f32_e32 v52, v52
	v_exp_f32_e32 v53, v53
	v_add_f32_e32 v5, v54, v55
	v_add_f32_e32 v2, v56, v57
	v_add_f32_e32 v5, v5, v58
	v_add_f32_e32 v2, v2, v59
	v_add_f32_e32 v5, v5, v60
	v_add_f32_e32 v2, v2, v61
	v_add_f32_e32 v5, v5, v62
	v_add_f32_e32 v2, v2, v63
	v_add_f32_e32 v5, v5, v64
	v_add_f32_e32 v2, v2, v65
	v_add_f32_e32 v5, v5, v66
	v_add_f32_e32 v2, v2, v67
	v_add_f32_e32 v5, v5, v68
	v_add_f32_e32 v2, v2, v69
	v_add_f32_e32 v5, v5, v38
	v_add_f32_e32 v2, v2, v39
	v_add_f32_e32 v5, v5, v40
	v_add_f32_e32 v2, v2, v41
	v_add_f32_e32 v5, v5, v42
	v_add_f32_e32 v2, v2, v43
	v_add_f32_e32 v5, v5, v44
	v_add_f32_e32 v2, v2, v45
	v_add_f32_e32 v5, v5, v46
	v_add_f32_e32 v2, v2, v47
	v_add_f32_e32 v5, v5, v48
	v_add_f32_e32 v2, v2, v49
	v_add_f32_e32 v5, v5, v50
	v_add_f32_e32 v2, v2, v51
	v_add_f32_e32 v5, v5, v52
	v_add_f32_e32 v2, v2, v53
	v_add_f32_e32 v5, v5, v2
	v_sub_f32_e32 v2, v113, v3
	v_exp_f32_e32 v2, v2
	v_mov_b32_e32 v113, v3
	s_nop 0
	v_fma_f32 v109, v109, v2, v5
	v_pk_mul_f32 v[36:37], v[36:37], v[2:3] op_sel_hi:[1,0]
	v_pk_mul_f32 v[34:35], v[34:35], v[2:3] op_sel_hi:[1,0]
	v_pk_mul_f32 v[32:33], v[32:33], v[2:3] op_sel_hi:[1,0]
	v_pk_mul_f32 v[30:31], v[30:31], v[2:3] op_sel_hi:[1,0]
	v_pk_mul_f32 v[28:29], v[28:29], v[2:3] op_sel_hi:[1,0]
	v_pk_mul_f32 v[26:27], v[26:27], v[2:3] op_sel_hi:[1,0]
	v_pk_mul_f32 v[24:25], v[24:25], v[2:3] op_sel_hi:[1,0]
	v_pk_mul_f32 v[22:23], v[22:23], v[2:3] op_sel_hi:[1,0]
	v_pk_mul_f32 v[20:21], v[20:21], v[2:3] op_sel_hi:[1,0]
	v_pk_mul_f32 v[18:19], v[18:19], v[2:3] op_sel_hi:[1,0]
	v_pk_mul_f32 v[16:17], v[16:17], v[2:3] op_sel_hi:[1,0]
	v_pk_mul_f32 v[14:15], v[14:15], v[2:3] op_sel_hi:[1,0]
	v_pk_mul_f32 v[12:13], v[12:13], v[2:3] op_sel_hi:[1,0]
	v_pk_mul_f32 v[10:11], v[10:11], v[2:3] op_sel_hi:[1,0]
	v_pk_mul_f32 v[8:9], v[8:9], v[2:3] op_sel_hi:[1,0]
	v_pk_mul_f32 v[6:7], v[6:7], v[2:3] op_sel_hi:[1,0]
	v_cvt_pk_bf16_f32 v54, v54, v55
	v_cvt_pk_bf16_f32 v55, v56, v57
	v_cvt_pk_bf16_f32 v56, v58, v59
	v_cvt_pk_bf16_f32 v57, v60, v61
	v_cvt_pk_bf16_f32 v58, v62, v63
	v_cvt_pk_bf16_f32 v59, v64, v65
	v_cvt_pk_bf16_f32 v60, v66, v67
	v_cvt_pk_bf16_f32 v61, v68, v69
	s_waitcnt lgkmcnt(0)
	v_mfma_f32_32x32x16_bf16 v[22:37], v[114:117], v[54:57], v[22:37]
	v_mfma_f32_32x32x16_bf16 v[6:21], v[118:121], v[54:57], v[6:21]
	v_cvt_pk_bf16_f32 v38, v38, v39
	v_cvt_pk_bf16_f32 v39, v40, v41
	v_cvt_pk_bf16_f32 v40, v42, v43
	v_cvt_pk_bf16_f32 v41, v44, v45
	v_mfma_f32_32x32x16_bf16 v[22:37], v[122:125], v[58:61], v[22:37]
	v_mfma_f32_32x32x16_bf16 v[6:21], v[126:129], v[58:61], v[6:21]
	v_cvt_pk_bf16_f32 v42, v46, v47
	v_cvt_pk_bf16_f32 v43, v48, v49
	v_cvt_pk_bf16_f32 v44, v50, v51
	v_cvt_pk_bf16_f32 v45, v52, v53
	v_mfma_f32_32x32x16_bf16 v[22:37], v[238:241], v[38:41], v[22:37]
	v_mfma_f32_32x32x16_bf16 v[6:21], v[242:245], v[38:41], v[6:21]
	v_mfma_f32_32x32x16_bf16 v[22:37], v[246:249], v[42:45], v[22:37]
	v_mfma_f32_32x32x16_bf16 v[6:21], v[250:253], v[42:45], v[6:21]
